# LDS bank conflicts: long-conv filter copies at an 84-slot stride (A-operand ds_read_b128 from 3-way to 2-way conflicts)
# speedup vs baseline: 1.0044x; 1.0034x over previous
; __device__ __forceinline__ void toeplitz_item(const Params& p, int layer, int half, int c, bf16* sm, int dry, unsigned* done_ctr) {
;     ...
;   const int aq = (8 - (r & 7)) & 7;
;   const int rt = (r + 7) >> 3;
;   bf16 wreg[3];
;   {
;     const int m0 = OFF - 128 * (-nb + 3) - 128;
; #pragma unroll
;     for (int i = 0; i < 3; ++i) { int x = tid + 256 * i; wreg[i] = x < 648 ? rho[m0 + x] : (bf16)0; }
;   }
;   for (int bt = 0; bt < nbatch; ++bt) {
;     const int D0 = -nb + 4 * bt;
;     __syncthreads();
; #pragma unroll
;     for (int i = 0; i < 3; ++i) {
;       const int x = tid + 256 * i;
;       if (x < 648) {
; #pragma unroll
;         for (int qq = 0; qq < 8; ++qq) {
;           const int y = x - qq;
;           if (y >= 0 && (y >> 3) < 80) sW[(qq * 83 + (y >> 3)) * 8 + (y & 7)] = wreg[i];
;         }
;       }
;     }
.LBB0_1146:
	s_or_b64 exec, exec, s[22:23]
	v_add_u32_e32 v10, -1, v4
	s_movk_i32 s40, 0x280
	v_and_b32_e32 v11, 7, v10
	v_cmp_gt_u32_e64 s[90:91], s40, v10
	v_add_u32_e32 v10, 0x297, v4
	v_and_b32_e32 v10, 0x7f8, v10
	v_lshlrev_b32_e32 v11, 1, v11
	v_add_u32_e32 v12, 6, v4
	v_lshl_or_b32 v119, v10, 1, v11
	v_add_u32_e32 v10, -2, v4
	v_and_b32_e32 v12, 7, v12
	v_cmp_gt_u32_e64 s[88:89], s40, v10
	v_add_u32_e32 v10, 0x52e, v4
	v_and_b32_e32 v10, 0xff8, v10
	v_lshlrev_b32_e32 v12, 1, v12
	v_add_u32_e32 v13, 5, v4
	v_lshl_or_b32 v118, v10, 1, v12
	v_add_u32_e32 v10, -3, v4
	v_and_b32_e32 v13, 7, v13
	v_cmp_gt_u32_e64 s[86:87], s40, v10
	v_add_u32_e32 v10, 0x7c5, v4
	v_and_b32_e32 v10, 0xff8, v10
	v_lshlrev_b32_e32 v13, 1, v13
	v_lshl_or_b32 v117, v10, 1, v13
	v_add_u32_e32 v10, -4, v4
	v_bitop3_b32 v15, v4, 4, 7 bitop3:0x6c
	v_cmp_gt_u32_e64 s[84:85], s40, v10
	v_add_u32_e32 v10, 0xa5c, v4
	v_and_b32_e32 v10, 0xff8, v10
	v_lshlrev_b32_e32 v15, 1, v15
	v_add_u32_e32 v16, 3, v4
	v_lshl_or_b32 v116, v10, 1, v15
	v_add_u32_e32 v10, -5, v4
	v_and_b32_e32 v16, 7, v16
	v_cmp_gt_u32_e64 s[82:83], s40, v10
	v_add_u32_e32 v10, 0xcf3, v4
	v_and_b32_e32 v10, 0x1ff8, v10
	v_lshlrev_b32_e32 v16, 1, v16
	v_add_u32_e32 v17, 2, v4
	v_lshl_or_b32 v115, v10, 1, v16
	v_add_u32_e32 v10, -6, v4
	v_and_b32_e32 v17, 7, v17
	v_cmp_gt_u32_e64 s[80:81], s40, v10
	v_add_u32_e32 v10, 0xf8a, v4
	v_and_b32_e32 v10, 0x1ff8, v10
	v_lshlrev_b32_e32 v17, 1, v17
	v_add_u32_e32 v18, 1, v4
	v_lshl_or_b32 v114, v10, 1, v17
	v_add_u32_e32 v10, -7, v4
	v_and_b32_e32 v18, 7, v18
	v_cmp_gt_u32_e64 s[78:79], s40, v10
	v_add_u32_e32 v10, 0x1221, v4
	v_add_u32_e32 v8, 0x100, v4
	v_and_b32_e32 v14, 7, v4
	v_and_b32_e32 v10, 0x17f8, v10
	v_lshlrev_b32_e32 v18, 1, v18
	v_lshlrev_b32_e32 v14, 1, v14
	v_lshl_or_b32 v113, v10, 1, v18
	v_and_b32_e32 v10, 0x3f8, v8
	v_lshl_or_b32 v112, v10, 1, v14
	v_add_u32_e32 v10, 0xff, v4
	v_cmp_gt_u32_e64 s[38:39], s40, v10
	v_add_u32_e32 v10, 0x397, v4
	v_and_b32_e32 v10, 0x3ff8, v10
	v_lshl_or_b32 v111, v10, 1, v11
	v_add_u32_e32 v10, 0xfe, v4
	v_cmp_gt_u32_e64 s[36:37], s40, v10
	v_add_u32_e32 v10, 0x62e, v4
	v_and_b32_e32 v10, 0x3ff8, v10
	v_lshl_or_b32 v110, v10, 1, v12
	v_add_u32_e32 v10, 0xfd, v4
	v_cmp_gt_u32_e64 s[34:35], s40, v10
	v_add_u32_e32 v10, 0x8c5, v4
	v_and_b32_e32 v10, 0x3ff8, v10
	v_lshl_or_b32 v109, v10, 1, v13
	v_add_u32_e32 v10, 0xfc, v4
	v_cmp_gt_u32_e64 s[30:31], s40, v10
	v_add_u32_e32 v10, 0xb5c, v4
	v_and_b32_e32 v10, 0x3ff8, v10
	v_lshl_or_b32 v108, v10, 1, v15
	v_add_u32_e32 v10, 0xfb, v4
	v_cmp_gt_u32_e64 s[28:29], s40, v10
	v_add_u32_e32 v10, 0xdf3, v4
	v_and_b32_e32 v10, 0x3ff8, v10
	v_lshl_or_b32 v107, v10, 1, v16
	v_add_u32_e32 v10, 0xfa, v4
	v_cmp_gt_u32_e64 s[26:27], s40, v10
	v_add_u32_e32 v10, 0x108a, v4
	v_and_b32_e32 v10, 0x3ff8, v10
	v_lshl_or_b32 v106, v10, 1, v17
	v_add_u32_e32 v10, 0xf9, v4
	v_cmp_gt_u32_e64 s[24:25], s40, v10
	v_add_u32_e32 v10, 0x1321, v4
	v_and_b32_e32 v10, 0x3ff8, v10
	v_lshl_or_b32 v105, v10, 1, v18
	v_and_b32_e32 v10, 0x3f8, v6
	v_lshl_or_b32 v104, v10, 1, v14
	v_add_u32_e32 v10, 0x1ff, v4
	v_cmp_gt_u32_e64 s[58:59], s40, v10
	v_add_u32_e32 v10, 0x497, v4
	v_and_b32_e32 v10, 0x3ff8, v10
	v_lshl_or_b32 v103, v10, 1, v11
	v_add_u32_e32 v10, 0x1fe, v4
	v_cmp_gt_u32_e64 s[56:57], s40, v10
	v_add_u32_e32 v10, 0x72e, v4
	v_and_b32_e32 v10, 0x3ff8, v10
	v_lshl_or_b32 v102, v10, 1, v12
	v_add_u32_e32 v10, 0x1fd, v4
	v_cmp_gt_u32_e64 s[96:97], s40, v10
	v_add_u32_e32 v10, 0x9c5, v4
	v_and_b32_e32 v10, 0x3ff8, v10
	v_lshl_or_b32 v101, v10, 1, v13
	v_add_u32_e32 v10, 0x1fc, v4
	v_cmp_gt_u32_e64 s[94:95], s40, v10
	v_add_u32_e32 v10, 0xc5c, v4
; __device__ __forceinline__ void toeplitz_item(const Params& p, int layer, int half, int c, bf16* sm, int dry, unsigned* done_ctr) {
;     ...
;   const int aq = (8 - (r & 7)) & 7;
;   const int rt = (r + 7) >> 3;
;   bf16 wreg[3];
;   {
;     const int m0 = OFF - 128 * (-nb + 3) - 128;
; #pragma unroll
;     for (int i = 0; i < 3; ++i) { int x = tid + 256 * i; wreg[i] = x < 648 ? rho[m0 + x] : (bf16)0; }
;   }
;   for (int bt = 0; bt < nbatch; ++bt) {
;     const int D0 = -nb + 4 * bt;
;     __syncthreads();
; #pragma unroll
;     for (int i = 0; i < 3; ++i) {
;       const int x = tid + 256 * i;
;       if (x < 648) {
; #pragma unroll
;         for (int qq = 0; qq < 8; ++qq) {
;           const int y = x - qq;
;           if (y >= 0 && (y >> 3) < 80) sW[(qq * 83 + (y >> 3)) * 8 + (y & 7)] = wreg[i];
;         }
;       }
;     }
;     __syncthreads();
;     if (bt + 1 < nbatch) {
;       const int m0 = OFF - 128 * (D0 + 4 + 3) - 128;
; #pragma unroll
;       for (int i = 0; i < 3; ++i) { int x = tid + 256 * i; wreg[i] = x < 648 ? rho[m0 + x] : (bf16)0; }
;     }
;     for (int Dl = 0; Dl < 4; ++Dl) {
;       const int D = D0 + Dl;
;       bool actv[2];
;       int bblk[2];
; #pragma unroll
;       for (int ni = 0; ni < 2; ++ni) {
;         const int nlo = 32 * wn + 64 * ni;
;         actv[ni] = half ? true : !((nlo + 31 - D < 0) || (nlo - D >= 128));
;         const int n = nlo + r;
;         const int src = n - D;
;         const bool valid = half ? ((unsigned)((n & 15) - D) < 16u) : ((unsigned)src < 128u);
;         bblk[ni] = valid ? src : 128;
;       }
;       if (!actv[0] && !actv[1]) continue;
;       const int tb = 16 * (3 - Dl) + 16 + hh - rt;
;       const bf16* ap0 = sW + (aq * 83 + tb - 4 * (2 * wm)) * 8;
;       const bf16* bp0 = sU + bblk[0] * 136 + 8 * hh;
;       const bf16* bp1 = sU + bblk[1] * 136 + 8 * hh;
	v_and_b32_e32 v10, 0x3ff8, v10
	v_lshl_or_b32 v100, v10, 1, v15
	v_add_u32_e32 v10, 0x1fb, v4
	v_cmp_gt_u32_e64 s[70:71], s40, v10
	v_add_u32_e32 v10, 0xef3, v4
	v_and_b32_e32 v10, 0x3ff8, v10
	v_lshl_or_b32 v99, v10, 1, v16
	v_add_u32_e32 v10, 0x1fa, v4
	v_cmp_gt_u32_e64 s[66:67], s40, v10
	v_add_u32_e32 v10, 0x118a, v4
	v_and_b32_e32 v94, 31, v4
	v_and_b32_e32 v10, 0x3ff8, v10
	v_sub_u32_e32 v3, 0, v4
	v_add_u32_e32 v9, 7, v94
	v_lshl_or_b32 v98, v10, 1, v17
	v_add_u32_e32 v10, 0x1f9, v4
	v_lshrrev_b32_e32 v0, 5, v0
	v_ashrrev_i32_e32 v88, 7, v4
	v_and_b32_e32 v3, 7, v3
	v_lshrrev_b32_e32 v9, 3, v9
	v_cmp_gt_u32_e32 vcc, s40, v4
	v_cmp_gt_u32_e64 s[20:21], s40, v8
	v_cmp_gt_u32_e64 s[22:23], s40, v6
	v_cmp_gt_u32_e64 s[64:65], s40, v10
	s_movk_i32 s40, 0x54
	v_add_u32_e32 v10, 0x1421, v4
	v_mad_u32_u24 v3, v3, s40, v0
	v_lshl_or_b32 v9, v88, 3, v9
	v_and_b32_e32 v10, 0x3ff8, v10
	v_sub_u32_e32 v3, v3, v9
	v_mov_b32_e32 v9, 0x400
	v_lshl_or_b32 v97, v10, 1, v18
	v_lshl_add_u32 v89, v3, 4, v9
	v_bfe_u32 v3, v4, 6, 1
	v_mul_u32_u24_e32 v10, 0x110, v94
	s_movk_i32 s40, 0x2200
	v_mad_u32_u24 v122, v3, s40, v10
	v_readlane_b32 s40, v254, 17
	s_add_u32 s2, s40, s2
	v_readlane_b32 s40, v254, 34
	v_and_b32_e32 v91, 15, v4
	v_and_b32_e32 v19, 0x3f8, v4
	v_ashrrev_i32_e32 v9, 31, v8
	s_addc_u32 s3, s40, s3
	s_mov_b32 s74, 0
	v_lshlrev_b32_e32 v90, 4, v0
	v_lshl_or_b32 v120, v19, 1, v14
	v_add_u32_e32 v123, 13, v91
	v_lshl_add_u64 v[82:83], v[6:7], 1, s[2:3]
	v_lshl_add_u64 v[84:85], v[8:9], 1, s[2:3]
	v_lshl_add_u64 v[86:87], v[4:5], 1, s[2:3]
	v_mov_b32_e32 v3, v2
	v_mov_b32_e32 v4, v2
	v_mov_b32_e32 v5, v2
	v_mov_b32_e32 v6, v2
	v_mov_b32_e32 v7, v2
	v_mov_b32_e32 v8, v2
	v_mov_b32_e32 v9, v2
	v_mov_b32_e32 v10, v2
	v_mov_b32_e32 v11, v2
	v_mov_b32_e32 v12, v2
	v_mov_b32_e32 v13, v2
	v_mov_b32_e32 v14, v2
	v_mov_b32_e32 v15, v2
	v_mov_b32_e32 v16, v2
	v_mov_b32_e32 v17, v2
	v_mov_b32_e32 v18, v2
	v_mov_b32_e32 v19, v2
	v_mov_b32_e32 v20, v2
	v_mov_b32_e32 v21, v2
	v_mov_b32_e32 v22, v2
	v_mov_b32_e32 v23, v2
	v_mov_b32_e32 v24, v2
	v_mov_b32_e32 v25, v2
	v_mov_b32_e32 v26, v2
	v_mov_b32_e32 v27, v2
	v_mov_b32_e32 v28, v2
	v_mov_b32_e32 v29, v2
	v_mov_b32_e32 v30, v2
	v_mov_b32_e32 v31, v2
	v_mov_b32_e32 v32, v2
	v_mov_b32_e32 v33, v2
	v_mov_b32_e32 v34, v2
	v_mov_b32_e32 v35, v2
	v_mov_b32_e32 v36, v2
	v_mov_b32_e32 v37, v2
	v_mov_b32_e32 v38, v2
	v_mov_b32_e32 v39, v2
	v_mov_b32_e32 v40, v2
	v_mov_b32_e32 v41, v2
	v_mov_b32_e32 v42, v2
	v_mov_b32_e32 v43, v2
	v_mov_b32_e32 v44, v2
	v_mov_b32_e32 v45, v2
	v_mov_b32_e32 v46, v2
	v_mov_b32_e32 v47, v2
	v_mov_b32_e32 v48, v2
	v_mov_b32_e32 v49, v2
	v_mov_b32_e32 v50, v2
	v_mov_b32_e32 v51, v2
	v_mov_b32_e32 v52, v2
	v_mov_b32_e32 v53, v2
	v_mov_b32_e32 v54, v2
	v_mov_b32_e32 v55, v2
	v_mov_b32_e32 v56, v2
	v_mov_b32_e32 v57, v2
	v_mov_b32_e32 v58, v2
	v_mov_b32_e32 v59, v2
	v_mov_b32_e32 v60, v2
	v_mov_b32_e32 v61, v2
	v_mov_b32_e32 v62, v2
	v_mov_b32_e32 v63, v2
	v_mov_b32_e32 v64, v2
	v_mov_b32_e32 v65, v2
	v_add_u32_e32 v119, 16, v119
	v_add_u32_e32 v118, 32, v118
	v_add_u32_e32 v117, 48, v117
	v_add_u32_e32 v116, 64, v116
	v_add_u32_e32 v115, 80, v115
	v_add_u32_e32 v114, 96, v114
	v_add_u32_e32 v113, 112, v113
	v_add_u32_e32 v111, 16, v111
	v_add_u32_e32 v110, 32, v110
	v_add_u32_e32 v109, 48, v109
	v_add_u32_e32 v108, 64, v108
	v_add_u32_e32 v107, 80, v107
	v_add_u32_e32 v106, 96, v106
	v_add_u32_e32 v105, 112, v105
	v_add_u32_e32 v103, 16, v103
	v_add_u32_e32 v102, 32, v102
	v_add_u32_e32 v101, 48, v101
	v_add_u32_e32 v100, 64, v100
	v_add_u32_e32 v99, 80, v99
	v_add_u32_e32 v98, 96, v98
	v_add_u32_e32 v97, 112, v97
	s_branch .LBB0_1148

; __device__ __forceinline__ void toeplitz_item(const Params& p, int layer, int half, int c, bf16* sm, int dry, unsigned* done_ctr) {
;     ...
;   const int aq = (8 - (r & 7)) & 7;
;   const int rt = (r + 7) >> 3;
;   bf16 wreg[3];
;   {
;     const int m0 = OFF - 128 * (-nb + 3) - 128;
; #pragma unroll
;     for (int i = 0; i < 3; ++i) { int x = tid + 256 * i; wreg[i] = x < 648 ? rho[m0 + x] : (bf16)0; }
;   }
;   for (int bt = 0; bt < nbatch; ++bt) {
;     const int D0 = -nb + 4 * bt;
;     __syncthreads();
; #pragma unroll
;     for (int i = 0; i < 3; ++i) {
;       const int x = tid + 256 * i;
;       if (x < 648) {
; #pragma unroll
;         for (int qq = 0; qq < 8; ++qq) {
;           const int y = x - qq;
;           if (y >= 0 && (y >> 3) < 80) sW[(qq * 83 + (y >> 3)) * 8 + (y & 7)] = wreg[i];
;         }
;       }
;     }
.LBB0_1368:
	s_or_b64 exec, exec, s[2:3]
	v_add_u32_e32 v3, 0x200, v2
	v_and_b32_e32 v5, 31, v2
	v_and_b32_e32 v12, 7, v2
	s_movk_i32 s2, 0x280
	v_add_u32_e32 v4, 0x100, v2
	v_sub_u32_e32 v7, 0, v2
	v_add_u32_e32 v8, 7, v5
	v_lshlrev_b32_e32 v12, 1, v12
	v_cmp_gt_u32_e64 s[22:23], s2, v3
	v_and_b32_e32 v3, 0x3f8, v3
	v_lshrrev_b32_e32 v103, 5, v6
	v_and_b32_e32 v6, 7, v7
	v_lshrrev_b32_e32 v7, 3, v8
	v_add_u32_e32 v8, -1, v2
	v_cmp_gt_u32_e64 s[46:47], s2, v4
	v_and_b32_e32 v4, 0x3f8, v4
	v_lshl_or_b32 v118, v3, 1, v12
	v_add_u32_e32 v3, 0x1ff, v2
	v_and_b32_e32 v9, 7, v8
	v_lshl_or_b32 v126, v4, 1, v12
	v_add_u32_e32 v4, 0xff, v2
	v_cmp_gt_u32_e64 s[20:21], s2, v3
	v_add_u32_e32 v3, 0x497, v2
	v_cmp_gt_u32_e64 s[90:91], s2, v8
	v_add_u32_e32 v8, 0x297, v2
	v_lshlrev_b32_e32 v9, 1, v9
	v_cmp_gt_u32_e64 s[38:39], s2, v4
	v_add_u32_e32 v4, 0x397, v2
	v_and_b32_e32 v3, 0x3ff8, v3
	v_add_u32_e32 v10, 6, v2
	v_and_b32_e32 v8, 0x7f8, v8
	v_and_b32_e32 v4, 0x3ff8, v4
	v_writelane_b32 v255, s20, 20
	v_lshl_or_b32 v117, v3, 1, v9
	v_add_u32_e32 v3, 0x1fe, v2
	v_and_b32_e32 v10, 7, v10
	v_lshl_or_b32 v133, v8, 1, v9
	v_add_u32_e32 v8, -2, v2
	v_lshl_or_b32 v125, v4, 1, v9
	v_add_u32_e32 v4, 0xfe, v2
	v_writelane_b32 v255, s21, 21
	v_cmp_gt_u32_e64 s[20:21], s2, v3
	v_add_u32_e32 v3, 0x72e, v2
	v_cmp_gt_u32_e64 s[88:89], s2, v8
	v_add_u32_e32 v8, 0x52e, v2
	v_lshlrev_b32_e32 v10, 1, v10
	v_cmp_gt_u32_e64 s[36:37], s2, v4
	v_add_u32_e32 v4, 0x62e, v2
	v_and_b32_e32 v3, 0x3ff8, v3
	v_add_u32_e32 v11, 5, v2
	v_and_b32_e32 v8, 0xff8, v8
	v_and_b32_e32 v4, 0x3ff8, v4
	v_writelane_b32 v255, s20, 22
	v_lshl_or_b32 v116, v3, 1, v10
	v_add_u32_e32 v3, 0x1fd, v2
	v_and_b32_e32 v11, 7, v11
	v_lshl_or_b32 v132, v8, 1, v10
	v_add_u32_e32 v8, -3, v2
	v_lshl_or_b32 v124, v4, 1, v10
	v_add_u32_e32 v4, 0xfd, v2
	v_writelane_b32 v255, s21, 23
	v_cmp_gt_u32_e64 s[20:21], s2, v3
	v_add_u32_e32 v3, 0x9c5, v2
	v_cmp_gt_u32_e64 s[86:87], s2, v8
	v_add_u32_e32 v8, 0x7c5, v2
	v_lshlrev_b32_e32 v11, 1, v11
	v_cmp_gt_u32_e64 s[34:35], s2, v4
	v_add_u32_e32 v4, 0x8c5, v2
	v_and_b32_e32 v3, 0x3ff8, v3
	v_and_b32_e32 v8, 0xff8, v8
	v_and_b32_e32 v4, 0x3ff8, v4
	v_lshl_or_b32 v115, v3, 1, v11
	v_add_u32_e32 v3, 0x1fc, v2
	v_bitop3_b32 v13, v2, 4, 7 bitop3:0x6c
	v_lshl_or_b32 v131, v8, 1, v11
	v_add_u32_e32 v8, -4, v2
	v_lshl_or_b32 v123, v4, 1, v11
	v_add_u32_e32 v4, 0xfc, v2
	v_cmp_gt_u32_e64 s[76:77], s2, v3
	v_add_u32_e32 v3, 0xc5c, v2
	v_cmp_gt_u32_e64 s[84:85], s2, v8
	v_add_u32_e32 v8, 0xa5c, v2
	v_lshlrev_b32_e32 v13, 1, v13
	v_cmp_gt_u32_e64 s[30:31], s2, v4
	v_add_u32_e32 v4, 0xb5c, v2
	v_and_b32_e32 v3, 0x3ff8, v3
	v_add_u32_e32 v14, 3, v2
	v_and_b32_e32 v8, 0xff8, v8
	v_and_b32_e32 v4, 0x3ff8, v4
	v_lshl_or_b32 v114, v3, 1, v13
	v_add_u32_e32 v3, 0x1fb, v2
	v_and_b32_e32 v14, 7, v14
	v_lshl_or_b32 v130, v8, 1, v13
	v_add_u32_e32 v8, -5, v2
	v_lshl_or_b32 v122, v4, 1, v13
	v_add_u32_e32 v4, 0xfb, v2
	v_cmp_gt_u32_e64 s[72:73], s2, v3
	v_add_u32_e32 v3, 0xef3, v2
	v_cmp_gt_u32_e64 s[82:83], s2, v8
	v_add_u32_e32 v8, 0xcf3, v2
	v_lshlrev_b32_e32 v14, 1, v14
	v_cmp_gt_u32_e64 s[28:29], s2, v4
	v_add_u32_e32 v4, 0xdf3, v2
	v_and_b32_e32 v3, 0x3ff8, v3
	v_add_u32_e32 v15, 2, v2
	v_and_b32_e32 v8, 0x1ff8, v8
	v_and_b32_e32 v4, 0x3ff8, v4
	v_lshl_or_b32 v113, v3, 1, v14
	v_add_u32_e32 v3, 0x1fa, v2
	v_and_b32_e32 v15, 7, v15
	v_lshl_or_b32 v129, v8, 1, v14
	v_add_u32_e32 v8, -6, v2
	v_lshl_or_b32 v121, v4, 1, v14
	v_add_u32_e32 v4, 0xfa, v2
	v_cmp_gt_u32_e64 s[66:67], s2, v3
	v_add_u32_e32 v3, 0x118a, v2
	v_cmp_gt_u32_e64 s[80:81], s2, v8
; __device__ __forceinline__ void toeplitz_item(const Params& p, int layer, int half, int c, bf16* sm, int dry, unsigned* done_ctr) {
;     ...
;   const int aq = (8 - (r & 7)) & 7;
;   const int rt = (r + 7) >> 3;
;   bf16 wreg[3];
;   {
;     const int m0 = OFF - 128 * (-nb + 3) - 128;
; #pragma unroll
;     for (int i = 0; i < 3; ++i) { int x = tid + 256 * i; wreg[i] = x < 648 ? rho[m0 + x] : (bf16)0; }
;   }
;   for (int bt = 0; bt < nbatch; ++bt) {
;     const int D0 = -nb + 4 * bt;
;     __syncthreads();
; #pragma unroll
;     for (int i = 0; i < 3; ++i) {
;       const int x = tid + 256 * i;
;       if (x < 648) {
; #pragma unroll
;         for (int qq = 0; qq < 8; ++qq) {
;           const int y = x - qq;
;           if (y >= 0 && (y >> 3) < 80) sW[(qq * 83 + (y >> 3)) * 8 + (y & 7)] = wreg[i];
;         }
;       }
;     }
;     __syncthreads();
;     if (bt + 1 < nbatch) {
;       const int m0 = OFF - 128 * (D0 + 4 + 3) - 128;
; #pragma unroll
;       for (int i = 0; i < 3; ++i) { int x = tid + 256 * i; wreg[i] = x < 648 ? rho[m0 + x] : (bf16)0; }
;     }
;     for (int Dl = 0; Dl < 4; ++Dl) {
;       const int D = D0 + Dl;
;       bool actv[2];
;       int bblk[2];
; #pragma unroll
;       for (int ni = 0; ni < 2; ++ni) {
;         const int nlo = 32 * wn + 64 * ni;
;         actv[ni] = half ? true : !((nlo + 31 - D < 0) || (nlo - D >= 128));
;         const int n = nlo + r;
;         const int src = n - D;
;         const bool valid = half ? ((unsigned)((n & 15) - D) < 16u) : ((unsigned)src < 128u);
;         bblk[ni] = valid ? src : 128;
;       }
;       if (!actv[0] && !actv[1]) continue;
;       const int tb = 16 * (3 - Dl) + 16 + hh - rt;
;       const bf16* ap0 = sW + (aq * 83 + tb - 4 * (2 * wm)) * 8;
;       const bf16* bp0 = sU + bblk[0] * 136 + 8 * hh;
;       const bf16* bp1 = sU + bblk[1] * 136 + 8 * hh;
	v_add_u32_e32 v8, 0xf8a, v2
	v_lshlrev_b32_e32 v15, 1, v15
	v_cmp_gt_u32_e64 s[26:27], s2, v4
	v_add_u32_e32 v4, 0x108a, v2
	v_and_b32_e32 v3, 0x3ff8, v3
	v_add_u32_e32 v16, 1, v2
	v_and_b32_e32 v8, 0x1ff8, v8
	v_and_b32_e32 v4, 0x3ff8, v4
	v_lshl_or_b32 v112, v3, 1, v15
	v_add_u32_e32 v3, 0x1f9, v2
	v_and_b32_e32 v16, 7, v16
	v_lshl_or_b32 v128, v8, 1, v15
	v_add_u32_e32 v8, -7, v2
	v_lshl_or_b32 v120, v4, 1, v15
	v_add_u32_e32 v4, 0xf9, v2
	v_cmp_gt_u32_e64 s[64:65], s2, v3
	v_add_u32_e32 v3, 0x1421, v2
	v_ashrrev_i32_e32 v104, 7, v2
	v_lshlrev_b32_e32 v0, 5, v0
	v_cmp_gt_u32_e64 s[58:59], s2, v2
	v_cmp_gt_u32_e64 s[78:79], s2, v8
	v_lshlrev_b32_e32 v16, 1, v16
	v_cmp_gt_u32_e64 s[24:25], s2, v4
	v_and_b32_e32 v3, 0x3ff8, v3
	s_movk_i32 s2, 0x54
	v_and_b32_e32 v107, 32, v0
	v_add_u32_e32 v8, 0x1221, v2
	v_add_u32_e32 v4, 0x1321, v2
	v_lshl_or_b32 v111, v3, 1, v16
	v_or_b32_e32 v138, 0xffffffc0, v0
	v_mad_u32_u24 v0, v6, s2, v103
	v_lshl_or_b32 v3, v104, 3, v7
	v_and_b32_e32 v17, 0x3f8, v2
	v_and_b32_e32 v8, 0x17f8, v8
	v_and_b32_e32 v4, 0x3ff8, v4
	v_sub_u32_e32 v0, v0, v3
	v_mov_b32_e32 v3, 0x400
	v_mov_b32_e32 v14, v1
	v_mov_b32_e32 v15, v1
	v_lshl_or_b32 v134, v17, 1, v12
	v_lshl_or_b32 v127, v8, 1, v16
	v_lshl_or_b32 v119, v4, 1, v16
	v_writelane_b32 v255, s20, 24
	v_lshl_add_u32 v108, v0, 4, v3
	v_or_b32_e32 v105, v107, v5
	v_add_u32_e32 v100, 0x7d00, v2
	v_mov_b32_e32 v0, v1
	v_mov_b32_e32 v2, v1
	v_mov_b32_e32 v3, v1
	v_mov_b32_e32 v4, v1
	v_mov_b32_e32 v5, v1
	v_mov_b32_e32 v6, v1
	v_mov_b32_e32 v7, v1
	v_mov_b32_e32 v8, v1
	v_mov_b32_e32 v9, v1
	v_mov_b32_e32 v10, v1
	v_mov_b32_e32 v11, v1
	v_mov_b32_e32 v12, v1
	v_mov_b32_e32 v13, v1
	v_mov_b64_e32 v[30:31], v[14:15]
	v_mov_b64_e32 v[46:47], v[14:15]
	v_mov_b64_e32 v[62:63], v[14:15]
	v_mov_b64_e32 v[78:79], v[14:15]
	s_mov_b32 s0, 0
	v_lshlrev_b32_e32 v106, 4, v103
	v_writelane_b32 v255, s21, 25
	v_or_b32_e32 v136, 31, v107
	v_or_b32_e32 v137, 0xffffff80, v107
	v_or_b32_e32 v109, 0x5f, v107
	s_mov_b32 s74, 0
	v_mov_b64_e32 v[28:29], v[12:13]
	v_mov_b64_e32 v[26:27], v[10:11]
	v_mov_b64_e32 v[24:25], v[8:9]
	v_mov_b64_e32 v[22:23], v[6:7]
	v_mov_b64_e32 v[20:21], v[4:5]
	v_mov_b64_e32 v[18:19], v[2:3]
	v_mov_b64_e32 v[16:17], v[0:1]
	v_mov_b64_e32 v[44:45], v[12:13]
	v_mov_b64_e32 v[42:43], v[10:11]
	v_mov_b64_e32 v[40:41], v[8:9]
	v_mov_b64_e32 v[38:39], v[6:7]
	v_mov_b64_e32 v[36:37], v[4:5]
	v_mov_b64_e32 v[34:35], v[2:3]
	v_mov_b64_e32 v[32:33], v[0:1]
	v_mov_b64_e32 v[60:61], v[12:13]
	v_mov_b64_e32 v[58:59], v[10:11]
	v_mov_b64_e32 v[56:57], v[8:9]
	v_mov_b64_e32 v[54:55], v[6:7]
	v_mov_b64_e32 v[52:53], v[4:5]
	v_mov_b64_e32 v[50:51], v[2:3]
	v_mov_b64_e32 v[48:49], v[0:1]
	v_mov_b64_e32 v[76:77], v[12:13]
	v_mov_b64_e32 v[74:75], v[10:11]
	v_mov_b64_e32 v[72:73], v[8:9]
	v_mov_b64_e32 v[70:71], v[6:7]
	v_mov_b64_e32 v[68:69], v[4:5]
	v_mov_b64_e32 v[66:67], v[2:3]
	v_mov_b64_e32 v[64:65], v[0:1]
	v_add_u32_e32 v133, 16, v133
	v_add_u32_e32 v132, 32, v132
	v_add_u32_e32 v131, 48, v131
	v_add_u32_e32 v130, 64, v130
	v_add_u32_e32 v129, 80, v129
	v_add_u32_e32 v128, 96, v128
	v_add_u32_e32 v127, 112, v127
	v_add_u32_e32 v125, 16, v125
	v_add_u32_e32 v124, 32, v124
	v_add_u32_e32 v123, 48, v123
	v_add_u32_e32 v122, 64, v122
	v_add_u32_e32 v121, 80, v121
	v_add_u32_e32 v120, 96, v120
	v_add_u32_e32 v119, 112, v119
	v_add_u32_e32 v117, 16, v117
	v_add_u32_e32 v116, 32, v116
	v_add_u32_e32 v115, 48, v115
	v_add_u32_e32 v114, 64, v114
	v_add_u32_e32 v113, 80, v113
	v_add_u32_e32 v112, 96, v112
	v_add_u32_e32 v111, 112, v111
	s_branch .LBB0_1371
